# w24+sigfix + counted publication of the phase-3 weight copies, checked together with the group arrival before phase 5 (formal ordering for bias1's cross-group reads)
# baseline (speedup 1.0000x reference)
; #define GSYNC() do { xcd_barrier(xbar); xcd_barrier(xbar); } while (0)
; #define GSYNC() xcd_barrier(xbar)
; #define REP(p) for (int rep_ = 0; rep_ < (((PROBE_MASK >> (p)) & 1) ? 2 : 1); ++rep_)
; __global__ void __launch_bounds__(NTHR, 2) fwd_megakernel(Args args) {
;     ...
;     weight_copy_items(args, lds, 16 * 96 + 32, 16 * 96 + 32 + 16 * 32 + 16 * 129 + 16 * 32, G);
;     GSYNC(); }
;     REP(4) { hgrn_scan_phase((const float*)(ws + WS_LST), (const float*)(ws + WS_DTOT), (float*)(ws + WS_SST), G);
.LBB0_346:
	s_or_b64 exec, exec, s[0:1]
	s_waitcnt vmcnt(0)
	s_barrier
	s_and_saveexec_b64 s[100:101], s[92:93]
	s_cbranch_execz .Lp4_polled
	v_mov_b32_e32 v250, 0
	v_mov_b32_e32 v251, 1
	global_atomic_add v250, v251, s[10:11] offset:3584

; #define GSYNC() do { xcd_barrier(xbar); xcd_barrier(xbar); } while (0)
; #define GSYNC() xcd_barrier(xbar)
; #define REP(p) for (int rep_ = 0; rep_ < (((PROBE_MASK >> (p)) & 1) ? 2 : 1); ++rep_)
; __global__ void __launch_bounds__(NTHR, 2) fwd_megakernel(Args args) {
;     ...
;     REP(4) { hgrn_scan_phase((const float*)(ws + WS_LST), (const float*)(ws + WS_DTOT), (float*)(ws + WS_SST), G);
;     GSYNC(); }
;     REP(5) { for (int u = blockIdx.x; u < 256; u += G) hgrn_unit<true>(lds, u, P0, args.in[5], args.in[7], nullptr, (const float*)(ws + WS_SST), nullptr, MIX);
;     bias1_phase((const bf16*)(ws + WS_W1IN), mod + 2 * 3072, (float*)(ws + WS_BIAS1), G);
.LBB0_403:
	s_or_b64 exec, exec, s[0:1]
	s_waitcnt vmcnt(0)
	s_barrier
	s_cmp_eq_u32 s6, 0x100
	s_cbranch_scc0 .Lg5_orig
	s_and_saveexec_b64 s[0:1], s[92:93]
	s_cbranch_execz .Lg5_done
	v_readlane_b32 s98, v249, 2
	s_lshr_b32 s98, s98, 5
	s_lshl_b32 s98, s98, 8
	s_add_i32 s98, s98, 0x1000
	v_mov_b32_e32 v250, s98
	v_mov_b32_e32 v251, 1
	global_atomic_add v250, v251, s[10:11]
	v_mov_b32_e32 v252, 0
.Lg5_poll:
	global_load_dword v251, v250, s[10:11] sc1
	global_load_dword v253, v252, s[10:11] offset:3584 sc1
	s_waitcnt vmcnt(0)
	v_cmp_gt_u32_e32 vcc, 32, v251
	s_nop 1
	s_cbranch_vccnz .Lg5_again
	v_cmp_gt_u32_e32 vcc, 0x100, v253
	s_nop 1
	s_cbranch_vccz .Lg5_pollend
.Lg5_again:
	s_sleep 1
	s_branch .Lg5_poll
